# strategy 7 instruction selection: v054 + F1/F7 K-loop LDS-DMA loads use the scalar-base form (global_load_lds_dwordx4 vOff, s[base]) instead of a 64-bit VALU add per load (16 VALU fewer per iteration
# baseline (speedup 1.0000x reference)
.LBB0_323:
	s_add_u32 s26, s24, 0xfffc0080
	s_addc_u32 s27, s25, -1
	s_add_i32 s36, 0, 0x10000
	s_cmp_eq_u32 s21, 12
	s_cselect_b32 s57, s17, s27
	s_cselect_b32 s56, s16, s26
	v_add_u32_e32 v142, s36, v161
	s_cselect_b32 s27, s19, s15
	s_cselect_b32 s26, s18, s13
	s_add_i32 s38, 0, 0x14000
	ds_read_b128 v[144:147], v142
	ds_read_b128 v[148:151], v142 offset:1024
	ds_read_b128 v[152:155], v142 offset:2048
	ds_read_b128 v[178:181], v142 offset:3072
	v_add_u32_e32 v142, s38, v161
	ds_read_b128 v[182:185], v142
	ds_read_b128 v[186:189], v142 offset:1024
	ds_read_b128 v[190:193], v142 offset:2048
	ds_read_b128 v[194:197], v142 offset:3072
	s_add_i32 m0, s68, 0xc000
	ds_read_b128 v[198:201], v177
	ds_read_b128 v[202:205], v177 offset:1024
	ds_read_b128 v[206:209], v177 offset:2048
	ds_read_b128 v[210:213], v177 offset:3072
	ds_read_b128 v[214:217], v177 offset:4096
	ds_read_b128 v[222:225], v177 offset:5120
	ds_read_b128 v[226:229], v177 offset:6144
	ds_read_b128 v[230:233], v177 offset:7168
	global_load_lds_dwordx4 v140, s[24:25]
	s_add_i32 m0, s68, 0xe000
	s_nop 0
	global_load_lds_dwordx4 v138, s[24:25]
	s_waitcnt vmcnt(8)
	s_waitcnt lgkmcnt(0)
	s_barrier
	v_mfma_i32_16x16x64_i8 v[126:129], v[144:147], v[198:201], v[126:129]
	v_mfma_i32_16x16x64_i8 v[118:121], v[152:155], v[198:201], v[118:121]
	v_mfma_i32_16x16x64_i8 v[110:113], v[144:147], v[206:209], v[110:113]
	v_mfma_i32_16x16x64_i8 v[102:105], v[152:155], v[206:209], v[102:105]
	v_mfma_i32_16x16x64_i8 v[94:97], v[144:147], v[214:217], v[94:97]
	v_mfma_i32_16x16x64_i8 v[86:89], v[152:155], v[214:217], v[86:89]
	v_mfma_i32_16x16x64_i8 v[78:81], v[144:147], v[226:229], v[78:81]
	v_mfma_i32_16x16x64_i8 v[70:73], v[152:155], v[226:229], v[70:73]
	v_mfma_i32_16x16x64_i8 v[126:129], v[148:151], v[202:205], v[126:129]
	v_mfma_i32_16x16x64_i8 v[118:121], v[178:181], v[202:205], v[118:121]
	v_mfma_i32_16x16x64_i8 v[110:113], v[148:151], v[210:213], v[110:113]
	v_mfma_i32_16x16x64_i8 v[102:105], v[178:181], v[210:213], v[102:105]
	v_mfma_i32_16x16x64_i8 v[94:97], v[148:151], v[222:225], v[94:97]
	v_mfma_i32_16x16x64_i8 v[86:89], v[178:181], v[222:225], v[86:89]
	v_mfma_i32_16x16x64_i8 v[78:81], v[148:151], v[230:233], v[78:81]
	v_mfma_i32_16x16x64_i8 v[70:73], v[178:181], v[230:233], v[70:73]
	v_mfma_i32_16x16x64_i8 v[122:125], v[182:185], v[198:201], v[122:125]
	v_mfma_i32_16x16x64_i8 v[114:117], v[190:193], v[198:201], v[114:117]
	v_mfma_i32_16x16x64_i8 v[106:109], v[182:185], v[206:209], v[106:109]
	v_mfma_i32_16x16x64_i8 v[98:101], v[190:193], v[206:209], v[98:101]
	v_mfma_i32_16x16x64_i8 v[90:93], v[182:185], v[214:217], v[90:93]
	v_mfma_i32_16x16x64_i8 v[82:85], v[190:193], v[214:217], v[82:85]
	v_mfma_i32_16x16x64_i8 v[74:77], v[182:185], v[226:229], v[74:77]
	v_mfma_i32_16x16x64_i8 v[66:69], v[190:193], v[226:229], v[66:69]
	v_mfma_i32_16x16x64_i8 v[122:125], v[186:189], v[202:205], v[122:125]
	v_mfma_i32_16x16x64_i8 v[114:117], v[194:197], v[202:205], v[114:117]
	v_mfma_i32_16x16x64_i8 v[106:109], v[186:189], v[210:213], v[106:109]
	v_mfma_i32_16x16x64_i8 v[98:101], v[194:197], v[210:213], v[98:101]
	v_mfma_i32_16x16x64_i8 v[90:93], v[186:189], v[222:225], v[90:93]
	v_mfma_i32_16x16x64_i8 v[82:85], v[194:197], v[222:225], v[82:85]
	v_mfma_i32_16x16x64_i8 v[74:77], v[186:189], v[230:233], v[74:77]
	v_mfma_i32_16x16x64_i8 v[66:69], v[194:197], v[230:233], v[66:69]
	s_barrier
	s_add_i32 s36, s36, s23
	s_mov_b32 m0, s36
	ds_read_b128 v[198:201], v177 offset:16384
	ds_read_b128 v[202:205], v177 offset:17408
	ds_read_b128 v[206:209], v177 offset:18432
	ds_read_b128 v[210:213], v177 offset:19456
	ds_read_b128 v[214:217], v177 offset:20480
	ds_read_b128 v[222:225], v177 offset:21504
	ds_read_b128 v[226:229], v177 offset:22528
	ds_read_b128 v[230:233], v177 offset:23552
	global_load_lds_dwordx4 v162, s[26:27]
	s_add_i32 m0, s36, 0x2000
	s_add_u32 s36, s26, 0x80000
	s_addc_u32 s37, s27, 0
	s_add_i32 s38, s38, s23
	global_load_lds_dwordx4 v134, s[26:27]
	s_mov_b32 m0, s38
	global_load_lds_dwordx4 v162, s[36:37]
	s_add_i32 m0, s38, 0x2000
	s_nop 0
	global_load_lds_dwordx4 v134, s[36:37]
	s_mov_b32 m0, s68
	s_nop 0
	global_load_lds_dwordx4 v130, s[56:57]
	s_mov_b32 m0, s69
	s_nop 0
	global_load_lds_dwordx4 v132, s[56:57]
	s_waitcnt vmcnt(8)
	s_waitcnt lgkmcnt(0)
	s_barrier
	v_mfma_i32_16x16x64_i8 v[62:65], v[144:147], v[198:201], v[62:65]
	v_mfma_i32_16x16x64_i8 v[54:57], v[152:155], v[198:201], v[54:57]
	v_mfma_i32_16x16x64_i8 v[46:49], v[144:147], v[206:209], v[46:49]
	v_mfma_i32_16x16x64_i8 v[38:41], v[152:155], v[206:209], v[38:41]
	v_mfma_i32_16x16x64_i8 v[30:33], v[144:147], v[214:217], v[30:33]
	v_mfma_i32_16x16x64_i8 v[22:25], v[152:155], v[214:217], v[22:25]
	v_mfma_i32_16x16x64_i8 v[14:17], v[144:147], v[226:229], v[14:17]
	v_mfma_i32_16x16x64_i8 v[6:9], v[152:155], v[226:229], v[6:9]
	v_mfma_i32_16x16x64_i8 v[62:65], v[148:151], v[202:205], v[62:65]
	v_mfma_i32_16x16x64_i8 v[54:57], v[178:181], v[202:205], v[54:57]
	v_mfma_i32_16x16x64_i8 v[46:49], v[148:151], v[210:213], v[46:49]
	v_mfma_i32_16x16x64_i8 v[38:41], v[178:181], v[210:213], v[38:41]
	v_mfma_i32_16x16x64_i8 v[30:33], v[148:151], v[222:225], v[30:33]
	v_mfma_i32_16x16x64_i8 v[22:25], v[178:181], v[222:225], v[22:25]
	v_mfma_i32_16x16x64_i8 v[14:17], v[148:151], v[230:233], v[14:17]
	v_mfma_i32_16x16x64_i8 v[6:9], v[178:181], v[230:233], v[6:9]
	v_mfma_i32_16x16x64_i8 v[58:61], v[182:185], v[198:201], v[58:61]
	v_mfma_i32_16x16x64_i8 v[50:53], v[190:193], v[198:201], v[50:53]
	v_mfma_i32_16x16x64_i8 v[42:45], v[182:185], v[206:209], v[42:45]
	v_mfma_i32_16x16x64_i8 v[34:37], v[190:193], v[206:209], v[34:37]
	v_mfma_i32_16x16x64_i8 v[26:29], v[182:185], v[214:217], v[26:29]
	v_mfma_i32_16x16x64_i8 v[18:21], v[190:193], v[214:217], v[18:21]
	v_mfma_i32_16x16x64_i8 v[10:13], v[182:185], v[226:229], v[10:13]
	v_mfma_i32_16x16x64_i8 v[2:5], v[190:193], v[226:229], v[2:5]
	v_mfma_i32_16x16x64_i8 v[58:61], v[186:189], v[202:205], v[58:61]
	v_mfma_i32_16x16x64_i8 v[50:53], v[194:197], v[202:205], v[50:53]
	v_mfma_i32_16x16x64_i8 v[42:45], v[186:189], v[210:213], v[42:45]
	v_mfma_i32_16x16x64_i8 v[34:37], v[194:197], v[210:213], v[34:37]
	v_mfma_i32_16x16x64_i8 v[26:29], v[186:189], v[222:225], v[26:29]
	v_mfma_i32_16x16x64_i8 v[18:21], v[194:197], v[222:225], v[18:21]
	v_mfma_i32_16x16x64_i8 v[10:13], v[186:189], v[230:233], v[10:13]
	v_mfma_i32_16x16x64_i8 v[2:5], v[194:197], v[230:233], v[2:5]
	s_barrier
	s_add_i32 s38, 0, 0x18000
	v_add_u32_e32 v142, s38, v161
	s_add_i32 s39, 0, 0x1c000
	ds_read_b128 v[144:147], v142
	ds_read_b128 v[148:151], v142 offset:1024
	ds_read_b128 v[152:155], v142 offset:2048
	ds_read_b128 v[178:181], v142 offset:3072
	v_add_u32_e32 v142, s39, v161
	ds_read_b128 v[182:185], v142
	ds_read_b128 v[186:189], v142 offset:1024
	ds_read_b128 v[190:193], v142 offset:2048
	ds_read_b128 v[194:197], v142 offset:3072
	s_add_u32 s36, s56, 0x40000
	s_addc_u32 s37, s57, 0
	s_mov_b32 m0, s70
	ds_read_b128 v[198:201], v177 offset:32768
	ds_read_b128 v[202:205], v177 offset:33792
	ds_read_b128 v[206:209], v177 offset:34816
	ds_read_b128 v[210:213], v177 offset:35840
	ds_read_b128 v[214:217], v177 offset:36864
	ds_read_b128 v[222:225], v177 offset:37888
	ds_read_b128 v[226:229], v177 offset:38912
	ds_read_b128 v[230:233], v177 offset:39936
	global_load_lds_dwordx4 v130, s[36:37]
	s_mov_b32 m0, s71
	s_nop 0
	global_load_lds_dwordx4 v132, s[36:37]
	s_waitcnt vmcnt(8)
	s_waitcnt lgkmcnt(0)
	s_barrier
	v_mfma_i32_16x16x64_i8 v[126:129], v[144:147], v[198:201], v[126:129]
	v_mfma_i32_16x16x64_i8 v[118:121], v[152:155], v[198:201], v[118:121]
	v_mfma_i32_16x16x64_i8 v[110:113], v[144:147], v[206:209], v[110:113]
	v_mfma_i32_16x16x64_i8 v[102:105], v[152:155], v[206:209], v[102:105]
	v_mfma_i32_16x16x64_i8 v[94:97], v[144:147], v[214:217], v[94:97]
	v_mfma_i32_16x16x64_i8 v[86:89], v[152:155], v[214:217], v[86:89]
	v_mfma_i32_16x16x64_i8 v[78:81], v[144:147], v[226:229], v[78:81]
	v_mfma_i32_16x16x64_i8 v[70:73], v[152:155], v[226:229], v[70:73]
	v_mfma_i32_16x16x64_i8 v[126:129], v[148:151], v[202:205], v[126:129]
	v_mfma_i32_16x16x64_i8 v[118:121], v[178:181], v[202:205], v[118:121]
	v_mfma_i32_16x16x64_i8 v[110:113], v[148:151], v[210:213], v[110:113]
	v_mfma_i32_16x16x64_i8 v[102:105], v[178:181], v[210:213], v[102:105]
	v_mfma_i32_16x16x64_i8 v[94:97], v[148:151], v[222:225], v[94:97]
	v_mfma_i32_16x16x64_i8 v[86:89], v[178:181], v[222:225], v[86:89]
	v_mfma_i32_16x16x64_i8 v[78:81], v[148:151], v[230:233], v[78:81]
	v_mfma_i32_16x16x64_i8 v[70:73], v[178:181], v[230:233], v[70:73]
	v_mfma_i32_16x16x64_i8 v[122:125], v[182:185], v[198:201], v[122:125]
	v_mfma_i32_16x16x64_i8 v[114:117], v[190:193], v[198:201], v[114:117]
	v_mfma_i32_16x16x64_i8 v[106:109], v[182:185], v[206:209], v[106:109]
	v_mfma_i32_16x16x64_i8 v[98:101], v[190:193], v[206:209], v[98:101]
	v_mfma_i32_16x16x64_i8 v[90:93], v[182:185], v[214:217], v[90:93]
	v_mfma_i32_16x16x64_i8 v[82:85], v[190:193], v[214:217], v[82:85]
	v_mfma_i32_16x16x64_i8 v[74:77], v[182:185], v[226:229], v[74:77]
	v_mfma_i32_16x16x64_i8 v[66:69], v[190:193], v[226:229], v[66:69]
	v_mfma_i32_16x16x64_i8 v[122:125], v[186:189], v[202:205], v[122:125]
	v_mfma_i32_16x16x64_i8 v[114:117], v[194:197], v[202:205], v[114:117]
	v_mfma_i32_16x16x64_i8 v[106:109], v[186:189], v[210:213], v[106:109]
	v_mfma_i32_16x16x64_i8 v[98:101], v[194:197], v[210:213], v[98:101]
	v_mfma_i32_16x16x64_i8 v[90:93], v[186:189], v[222:225], v[90:93]
	v_mfma_i32_16x16x64_i8 v[82:85], v[194:197], v[222:225], v[82:85]
	v_mfma_i32_16x16x64_i8 v[74:77], v[186:189], v[230:233], v[74:77]
	v_mfma_i32_16x16x64_i8 v[66:69], v[194:197], v[230:233], v[66:69]
	s_barrier
	s_add_i32 s36, s38, s23
	s_mov_b32 m0, s36
	ds_read_b128 v[198:201], v177 offset:49152
	ds_read_b128 v[202:205], v177 offset:50176
	ds_read_b128 v[206:209], v177 offset:51200
	ds_read_b128 v[210:213], v177 offset:52224
	ds_read_b128 v[214:217], v177 offset:53248
	ds_read_b128 v[222:225], v177 offset:54272
	ds_read_b128 v[226:229], v177 offset:55296
	ds_read_b128 v[230:233], v177 offset:56320
	s_add_u32 s100, s26, s44
	s_addc_u32 s101, s27, s45
	global_load_lds_dwordx4 v162, s[100:101]
	s_add_i32 m0, s36, 0x2000
	s_add_u32 s26, s26, 0x80080
	s_addc_u32 s27, s27, 0
	s_add_i32 s36, s39, s23
	global_load_lds_dwordx4 v134, s[100:101]
	s_mov_b32 m0, s36
	s_nop 0
	global_load_lds_dwordx4 v162, s[26:27]
	s_add_i32 m0, s36, 0x2000
	s_nop 0
	global_load_lds_dwordx4 v134, s[26:27]
	s_mov_b32 m0, s72
	s_nop 0
	s_add_u32 s100, s56, s44
	s_addc_u32 s101, s57, s45
	global_load_lds_dwordx4 v130, s[100:101]
	s_mov_b32 m0, s73
	s_nop 0
	global_load_lds_dwordx4 v132, s[100:101]
	s_waitcnt vmcnt(8)
	s_waitcnt lgkmcnt(0)
	s_barrier
	v_mfma_i32_16x16x64_i8 v[62:65], v[144:147], v[198:201], v[62:65]
	v_mfma_i32_16x16x64_i8 v[54:57], v[152:155], v[198:201], v[54:57]
	v_mfma_i32_16x16x64_i8 v[46:49], v[144:147], v[206:209], v[46:49]
	v_mfma_i32_16x16x64_i8 v[38:41], v[152:155], v[206:209], v[38:41]
	v_mfma_i32_16x16x64_i8 v[30:33], v[144:147], v[214:217], v[30:33]
	v_mfma_i32_16x16x64_i8 v[22:25], v[152:155], v[214:217], v[22:25]
	v_mfma_i32_16x16x64_i8 v[14:17], v[144:147], v[226:229], v[14:17]
	v_mfma_i32_16x16x64_i8 v[6:9], v[152:155], v[226:229], v[6:9]
	v_mfma_i32_16x16x64_i8 v[62:65], v[148:151], v[202:205], v[62:65]
	v_mfma_i32_16x16x64_i8 v[54:57], v[178:181], v[202:205], v[54:57]
	v_mfma_i32_16x16x64_i8 v[46:49], v[148:151], v[210:213], v[46:49]
	v_mfma_i32_16x16x64_i8 v[38:41], v[178:181], v[210:213], v[38:41]
	v_mfma_i32_16x16x64_i8 v[30:33], v[148:151], v[222:225], v[30:33]
	v_mfma_i32_16x16x64_i8 v[22:25], v[178:181], v[222:225], v[22:25]
	v_mfma_i32_16x16x64_i8 v[14:17], v[148:151], v[230:233], v[14:17]
	v_mfma_i32_16x16x64_i8 v[6:9], v[178:181], v[230:233], v[6:9]
	v_mfma_i32_16x16x64_i8 v[58:61], v[182:185], v[198:201], v[58:61]
	v_mfma_i32_16x16x64_i8 v[50:53], v[190:193], v[198:201], v[50:53]
	v_mfma_i32_16x16x64_i8 v[42:45], v[182:185], v[206:209], v[42:45]
	v_mfma_i32_16x16x64_i8 v[34:37], v[190:193], v[206:209], v[34:37]
	v_mfma_i32_16x16x64_i8 v[26:29], v[182:185], v[214:217], v[26:29]
	v_mfma_i32_16x16x64_i8 v[18:21], v[190:193], v[214:217], v[18:21]
	v_mfma_i32_16x16x64_i8 v[10:13], v[182:185], v[226:229], v[10:13]
	v_mfma_i32_16x16x64_i8 v[2:5], v[190:193], v[226:229], v[2:5]
	v_mfma_i32_16x16x64_i8 v[58:61], v[186:189], v[202:205], v[58:61]
	v_mfma_i32_16x16x64_i8 v[50:53], v[194:197], v[202:205], v[50:53]
	v_mfma_i32_16x16x64_i8 v[42:45], v[186:189], v[210:213], v[42:45]
	v_mfma_i32_16x16x64_i8 v[34:37], v[194:197], v[210:213], v[34:37]
	v_mfma_i32_16x16x64_i8 v[26:29], v[186:189], v[222:225], v[26:29]
	v_mfma_i32_16x16x64_i8 v[18:21], v[194:197], v[222:225], v[18:21]
	v_mfma_i32_16x16x64_i8 v[10:13], v[186:189], v[230:233], v[10:13]
	v_mfma_i32_16x16x64_i8 v[2:5], v[194:197], v[230:233], v[2:5]
	s_barrier
	s_add_i32 s21, s21, 2
	s_add_u32 s13, s13, 0x100
	s_addc_u32 s15, s15, 0
	s_add_u32 s24, s24, 0x100
	s_addc_u32 s25, s25, 0
	s_cmp_gt_u32 s21, 13
	s_cbranch_scc0 .LBB0_323
	s_and_b64 vcc, exec, s[10:11]
	s_cbranch_vccz .LBB0_326
	s_barrier

.LBB0_1332:
	s_add_u32 s26, s24, 0xfffc0080
	s_addc_u32 s27, s25, -1
	s_add_i32 s36, 0, 0x10000
	s_cmp_eq_u32 s21, 12
	s_cselect_b32 s57, s17, s27
	s_cselect_b32 s56, s16, s26
	v_add_u32_e32 v142, s36, v161
	s_cselect_b32 s27, s19, s15
	s_cselect_b32 s26, s18, s13
	s_add_i32 s38, 0, 0x14000
	ds_read_b128 v[144:147], v142
	ds_read_b128 v[148:151], v142 offset:1024
	ds_read_b128 v[152:155], v142 offset:2048
	ds_read_b128 v[178:181], v142 offset:3072
	v_add_u32_e32 v142, s38, v161
	ds_read_b128 v[182:185], v142
	ds_read_b128 v[186:189], v142 offset:1024
	ds_read_b128 v[190:193], v142 offset:2048
	ds_read_b128 v[194:197], v142 offset:3072
	s_add_i32 m0, s69, 0xc000
	ds_read_b128 v[198:201], v177
	ds_read_b128 v[202:205], v177 offset:1024
	ds_read_b128 v[206:209], v177 offset:2048
	ds_read_b128 v[210:213], v177 offset:3072
	ds_read_b128 v[214:217], v177 offset:4096
	ds_read_b128 v[222:225], v177 offset:5120
	ds_read_b128 v[226:229], v177 offset:6144
	ds_read_b128 v[230:233], v177 offset:7168
	global_load_lds_dwordx4 v140, s[24:25]
	s_add_i32 m0, s69, 0xe000
	s_nop 0
	global_load_lds_dwordx4 v138, s[24:25]
	s_waitcnt vmcnt(8)
	s_waitcnt lgkmcnt(0)
	s_barrier
	v_mfma_i32_16x16x64_i8 v[126:129], v[144:147], v[198:201], v[126:129]
	v_mfma_i32_16x16x64_i8 v[118:121], v[152:155], v[198:201], v[118:121]
	v_mfma_i32_16x16x64_i8 v[110:113], v[144:147], v[206:209], v[110:113]
	v_mfma_i32_16x16x64_i8 v[102:105], v[152:155], v[206:209], v[102:105]
	v_mfma_i32_16x16x64_i8 v[94:97], v[144:147], v[214:217], v[94:97]
	v_mfma_i32_16x16x64_i8 v[86:89], v[152:155], v[214:217], v[86:89]
	v_mfma_i32_16x16x64_i8 v[78:81], v[144:147], v[226:229], v[78:81]
	v_mfma_i32_16x16x64_i8 v[70:73], v[152:155], v[226:229], v[70:73]
	v_mfma_i32_16x16x64_i8 v[126:129], v[148:151], v[202:205], v[126:129]
	v_mfma_i32_16x16x64_i8 v[118:121], v[178:181], v[202:205], v[118:121]
	v_mfma_i32_16x16x64_i8 v[110:113], v[148:151], v[210:213], v[110:113]
	v_mfma_i32_16x16x64_i8 v[102:105], v[178:181], v[210:213], v[102:105]
	v_mfma_i32_16x16x64_i8 v[94:97], v[148:151], v[222:225], v[94:97]
	v_mfma_i32_16x16x64_i8 v[86:89], v[178:181], v[222:225], v[86:89]
	v_mfma_i32_16x16x64_i8 v[78:81], v[148:151], v[230:233], v[78:81]
	v_mfma_i32_16x16x64_i8 v[70:73], v[178:181], v[230:233], v[70:73]
	v_mfma_i32_16x16x64_i8 v[122:125], v[182:185], v[198:201], v[122:125]
	v_mfma_i32_16x16x64_i8 v[114:117], v[190:193], v[198:201], v[114:117]
	v_mfma_i32_16x16x64_i8 v[106:109], v[182:185], v[206:209], v[106:109]
	v_mfma_i32_16x16x64_i8 v[98:101], v[190:193], v[206:209], v[98:101]
	v_mfma_i32_16x16x64_i8 v[90:93], v[182:185], v[214:217], v[90:93]
	v_mfma_i32_16x16x64_i8 v[82:85], v[190:193], v[214:217], v[82:85]
	v_mfma_i32_16x16x64_i8 v[74:77], v[182:185], v[226:229], v[74:77]
	v_mfma_i32_16x16x64_i8 v[66:69], v[190:193], v[226:229], v[66:69]
	v_mfma_i32_16x16x64_i8 v[122:125], v[186:189], v[202:205], v[122:125]
	v_mfma_i32_16x16x64_i8 v[114:117], v[194:197], v[202:205], v[114:117]
	v_mfma_i32_16x16x64_i8 v[106:109], v[186:189], v[210:213], v[106:109]
	v_mfma_i32_16x16x64_i8 v[98:101], v[194:197], v[210:213], v[98:101]
	v_mfma_i32_16x16x64_i8 v[90:93], v[186:189], v[222:225], v[90:93]
	v_mfma_i32_16x16x64_i8 v[82:85], v[194:197], v[222:225], v[82:85]
	v_mfma_i32_16x16x64_i8 v[74:77], v[186:189], v[230:233], v[74:77]
	v_mfma_i32_16x16x64_i8 v[66:69], v[194:197], v[230:233], v[66:69]
	s_barrier
	s_add_i32 s36, s36, s23
	s_mov_b32 m0, s36
	ds_read_b128 v[198:201], v177 offset:16384
	ds_read_b128 v[202:205], v177 offset:17408
	ds_read_b128 v[206:209], v177 offset:18432
	ds_read_b128 v[210:213], v177 offset:19456
	ds_read_b128 v[214:217], v177 offset:20480
	ds_read_b128 v[222:225], v177 offset:21504
	ds_read_b128 v[226:229], v177 offset:22528
	ds_read_b128 v[230:233], v177 offset:23552
	global_load_lds_dwordx4 v162, s[26:27]
	s_add_i32 m0, s36, 0x2000
	s_add_u32 s36, s26, 0x80000
	s_addc_u32 s37, s27, 0
	s_add_i32 s38, s38, s23
	global_load_lds_dwordx4 v134, s[26:27]
	s_mov_b32 m0, s38
	global_load_lds_dwordx4 v162, s[36:37]
	s_add_i32 m0, s38, 0x2000
	s_nop 0
	global_load_lds_dwordx4 v134, s[36:37]
	s_mov_b32 m0, s69
	s_nop 0
	global_load_lds_dwordx4 v130, s[56:57]
	s_mov_b32 m0, s70
	s_nop 0
	global_load_lds_dwordx4 v132, s[56:57]
	s_waitcnt vmcnt(8)
	s_waitcnt lgkmcnt(0)
	s_barrier
	v_mfma_i32_16x16x64_i8 v[62:65], v[144:147], v[198:201], v[62:65]
	v_mfma_i32_16x16x64_i8 v[54:57], v[152:155], v[198:201], v[54:57]
	v_mfma_i32_16x16x64_i8 v[46:49], v[144:147], v[206:209], v[46:49]
	v_mfma_i32_16x16x64_i8 v[38:41], v[152:155], v[206:209], v[38:41]
	v_mfma_i32_16x16x64_i8 v[30:33], v[144:147], v[214:217], v[30:33]
	v_mfma_i32_16x16x64_i8 v[22:25], v[152:155], v[214:217], v[22:25]
	v_mfma_i32_16x16x64_i8 v[14:17], v[144:147], v[226:229], v[14:17]
	v_mfma_i32_16x16x64_i8 v[6:9], v[152:155], v[226:229], v[6:9]
	v_mfma_i32_16x16x64_i8 v[62:65], v[148:151], v[202:205], v[62:65]
	v_mfma_i32_16x16x64_i8 v[54:57], v[178:181], v[202:205], v[54:57]
	v_mfma_i32_16x16x64_i8 v[46:49], v[148:151], v[210:213], v[46:49]
	v_mfma_i32_16x16x64_i8 v[38:41], v[178:181], v[210:213], v[38:41]
	v_mfma_i32_16x16x64_i8 v[30:33], v[148:151], v[222:225], v[30:33]
	v_mfma_i32_16x16x64_i8 v[22:25], v[178:181], v[222:225], v[22:25]
	v_mfma_i32_16x16x64_i8 v[14:17], v[148:151], v[230:233], v[14:17]
	v_mfma_i32_16x16x64_i8 v[6:9], v[178:181], v[230:233], v[6:9]
	v_mfma_i32_16x16x64_i8 v[58:61], v[182:185], v[198:201], v[58:61]
	v_mfma_i32_16x16x64_i8 v[50:53], v[190:193], v[198:201], v[50:53]
	v_mfma_i32_16x16x64_i8 v[42:45], v[182:185], v[206:209], v[42:45]
	v_mfma_i32_16x16x64_i8 v[34:37], v[190:193], v[206:209], v[34:37]
	v_mfma_i32_16x16x64_i8 v[26:29], v[182:185], v[214:217], v[26:29]
	v_mfma_i32_16x16x64_i8 v[18:21], v[190:193], v[214:217], v[18:21]
	v_mfma_i32_16x16x64_i8 v[10:13], v[182:185], v[226:229], v[10:13]
	v_mfma_i32_16x16x64_i8 v[2:5], v[190:193], v[226:229], v[2:5]
	v_mfma_i32_16x16x64_i8 v[58:61], v[186:189], v[202:205], v[58:61]
	v_mfma_i32_16x16x64_i8 v[50:53], v[194:197], v[202:205], v[50:53]
	v_mfma_i32_16x16x64_i8 v[42:45], v[186:189], v[210:213], v[42:45]
	v_mfma_i32_16x16x64_i8 v[34:37], v[194:197], v[210:213], v[34:37]
	v_mfma_i32_16x16x64_i8 v[26:29], v[186:189], v[222:225], v[26:29]
	v_mfma_i32_16x16x64_i8 v[18:21], v[194:197], v[222:225], v[18:21]
	v_mfma_i32_16x16x64_i8 v[10:13], v[186:189], v[230:233], v[10:13]
	v_mfma_i32_16x16x64_i8 v[2:5], v[194:197], v[230:233], v[2:5]
	s_barrier
	s_add_i32 s38, 0, 0x18000
	v_add_u32_e32 v142, s38, v161
	s_add_i32 s39, 0, 0x1c000
	ds_read_b128 v[144:147], v142
	ds_read_b128 v[148:151], v142 offset:1024
	ds_read_b128 v[152:155], v142 offset:2048
	ds_read_b128 v[178:181], v142 offset:3072
	v_add_u32_e32 v142, s39, v161
	ds_read_b128 v[182:185], v142
	ds_read_b128 v[186:189], v142 offset:1024
	ds_read_b128 v[190:193], v142 offset:2048
	ds_read_b128 v[194:197], v142 offset:3072
	s_add_u32 s36, s56, 0x40000
	s_addc_u32 s37, s57, 0
	s_mov_b32 m0, s71
	ds_read_b128 v[198:201], v177 offset:32768
	ds_read_b128 v[202:205], v177 offset:33792
	ds_read_b128 v[206:209], v177 offset:34816
	ds_read_b128 v[210:213], v177 offset:35840
	ds_read_b128 v[214:217], v177 offset:36864
	ds_read_b128 v[222:225], v177 offset:37888
	ds_read_b128 v[226:229], v177 offset:38912
	ds_read_b128 v[230:233], v177 offset:39936
	global_load_lds_dwordx4 v130, s[36:37]
	s_mov_b32 m0, s72
	s_nop 0
	global_load_lds_dwordx4 v132, s[36:37]
	s_waitcnt vmcnt(8)
	s_waitcnt lgkmcnt(0)
	s_barrier
	v_mfma_i32_16x16x64_i8 v[126:129], v[144:147], v[198:201], v[126:129]
	v_mfma_i32_16x16x64_i8 v[118:121], v[152:155], v[198:201], v[118:121]
	v_mfma_i32_16x16x64_i8 v[110:113], v[144:147], v[206:209], v[110:113]
	v_mfma_i32_16x16x64_i8 v[102:105], v[152:155], v[206:209], v[102:105]
	v_mfma_i32_16x16x64_i8 v[94:97], v[144:147], v[214:217], v[94:97]
	v_mfma_i32_16x16x64_i8 v[86:89], v[152:155], v[214:217], v[86:89]
	v_mfma_i32_16x16x64_i8 v[78:81], v[144:147], v[226:229], v[78:81]
	v_mfma_i32_16x16x64_i8 v[70:73], v[152:155], v[226:229], v[70:73]
	v_mfma_i32_16x16x64_i8 v[126:129], v[148:151], v[202:205], v[126:129]
	v_mfma_i32_16x16x64_i8 v[118:121], v[178:181], v[202:205], v[118:121]
	v_mfma_i32_16x16x64_i8 v[110:113], v[148:151], v[210:213], v[110:113]
	v_mfma_i32_16x16x64_i8 v[102:105], v[178:181], v[210:213], v[102:105]
	v_mfma_i32_16x16x64_i8 v[94:97], v[148:151], v[222:225], v[94:97]
	v_mfma_i32_16x16x64_i8 v[86:89], v[178:181], v[222:225], v[86:89]
	v_mfma_i32_16x16x64_i8 v[78:81], v[148:151], v[230:233], v[78:81]
	v_mfma_i32_16x16x64_i8 v[70:73], v[178:181], v[230:233], v[70:73]
	v_mfma_i32_16x16x64_i8 v[122:125], v[182:185], v[198:201], v[122:125]
	v_mfma_i32_16x16x64_i8 v[114:117], v[190:193], v[198:201], v[114:117]
	v_mfma_i32_16x16x64_i8 v[106:109], v[182:185], v[206:209], v[106:109]
	v_mfma_i32_16x16x64_i8 v[98:101], v[190:193], v[206:209], v[98:101]
	v_mfma_i32_16x16x64_i8 v[90:93], v[182:185], v[214:217], v[90:93]
	v_mfma_i32_16x16x64_i8 v[82:85], v[190:193], v[214:217], v[82:85]
	v_mfma_i32_16x16x64_i8 v[74:77], v[182:185], v[226:229], v[74:77]
	v_mfma_i32_16x16x64_i8 v[66:69], v[190:193], v[226:229], v[66:69]
	v_mfma_i32_16x16x64_i8 v[122:125], v[186:189], v[202:205], v[122:125]
	v_mfma_i32_16x16x64_i8 v[114:117], v[194:197], v[202:205], v[114:117]
	v_mfma_i32_16x16x64_i8 v[106:109], v[186:189], v[210:213], v[106:109]
	v_mfma_i32_16x16x64_i8 v[98:101], v[194:197], v[210:213], v[98:101]
	v_mfma_i32_16x16x64_i8 v[90:93], v[186:189], v[222:225], v[90:93]
	v_mfma_i32_16x16x64_i8 v[82:85], v[194:197], v[222:225], v[82:85]
	v_mfma_i32_16x16x64_i8 v[74:77], v[186:189], v[230:233], v[74:77]
	v_mfma_i32_16x16x64_i8 v[66:69], v[194:197], v[230:233], v[66:69]
	s_barrier
	s_add_i32 s36, s38, s23
	s_mov_b32 m0, s36
	ds_read_b128 v[198:201], v177 offset:49152
	ds_read_b128 v[202:205], v177 offset:50176
	ds_read_b128 v[206:209], v177 offset:51200
	ds_read_b128 v[210:213], v177 offset:52224
	ds_read_b128 v[214:217], v177 offset:53248
	ds_read_b128 v[222:225], v177 offset:54272
	ds_read_b128 v[226:229], v177 offset:55296
	ds_read_b128 v[230:233], v177 offset:56320
	s_add_u32 s100, s26, s44
	s_addc_u32 s101, s27, s45
	global_load_lds_dwordx4 v162, s[100:101]
	s_add_i32 m0, s36, 0x2000
	s_add_u32 s26, s26, 0x80080
	s_addc_u32 s27, s27, 0
	s_add_i32 s36, s39, s23
	global_load_lds_dwordx4 v134, s[100:101]
	s_mov_b32 m0, s36
	s_nop 0
	global_load_lds_dwordx4 v162, s[26:27]
	s_add_i32 m0, s36, 0x2000
	s_nop 0
	global_load_lds_dwordx4 v134, s[26:27]
	s_mov_b32 m0, s73
	s_nop 0
	s_add_u32 s100, s56, s44
	s_addc_u32 s101, s57, s45
	global_load_lds_dwordx4 v130, s[100:101]
	s_mov_b32 m0, s74
	s_nop 0
	global_load_lds_dwordx4 v132, s[100:101]
	s_waitcnt vmcnt(8)
	s_waitcnt lgkmcnt(0)
	s_barrier
	v_mfma_i32_16x16x64_i8 v[62:65], v[144:147], v[198:201], v[62:65]
	v_mfma_i32_16x16x64_i8 v[54:57], v[152:155], v[198:201], v[54:57]
	v_mfma_i32_16x16x64_i8 v[46:49], v[144:147], v[206:209], v[46:49]
	v_mfma_i32_16x16x64_i8 v[38:41], v[152:155], v[206:209], v[38:41]
	v_mfma_i32_16x16x64_i8 v[30:33], v[144:147], v[214:217], v[30:33]
	v_mfma_i32_16x16x64_i8 v[22:25], v[152:155], v[214:217], v[22:25]
	v_mfma_i32_16x16x64_i8 v[14:17], v[144:147], v[226:229], v[14:17]
	v_mfma_i32_16x16x64_i8 v[6:9], v[152:155], v[226:229], v[6:9]
	v_mfma_i32_16x16x64_i8 v[62:65], v[148:151], v[202:205], v[62:65]
	v_mfma_i32_16x16x64_i8 v[54:57], v[178:181], v[202:205], v[54:57]
	v_mfma_i32_16x16x64_i8 v[46:49], v[148:151], v[210:213], v[46:49]
	v_mfma_i32_16x16x64_i8 v[38:41], v[178:181], v[210:213], v[38:41]
	v_mfma_i32_16x16x64_i8 v[30:33], v[148:151], v[222:225], v[30:33]
	v_mfma_i32_16x16x64_i8 v[22:25], v[178:181], v[222:225], v[22:25]
	v_mfma_i32_16x16x64_i8 v[14:17], v[148:151], v[230:233], v[14:17]
	v_mfma_i32_16x16x64_i8 v[6:9], v[178:181], v[230:233], v[6:9]
	v_mfma_i32_16x16x64_i8 v[58:61], v[182:185], v[198:201], v[58:61]
	v_mfma_i32_16x16x64_i8 v[50:53], v[190:193], v[198:201], v[50:53]
	v_mfma_i32_16x16x64_i8 v[42:45], v[182:185], v[206:209], v[42:45]
	v_mfma_i32_16x16x64_i8 v[34:37], v[190:193], v[206:209], v[34:37]
	v_mfma_i32_16x16x64_i8 v[26:29], v[182:185], v[214:217], v[26:29]
	v_mfma_i32_16x16x64_i8 v[18:21], v[190:193], v[214:217], v[18:21]
	v_mfma_i32_16x16x64_i8 v[10:13], v[182:185], v[226:229], v[10:13]
	v_mfma_i32_16x16x64_i8 v[2:5], v[190:193], v[226:229], v[2:5]
	v_mfma_i32_16x16x64_i8 v[58:61], v[186:189], v[202:205], v[58:61]
	v_mfma_i32_16x16x64_i8 v[50:53], v[194:197], v[202:205], v[50:53]
	v_mfma_i32_16x16x64_i8 v[42:45], v[186:189], v[210:213], v[42:45]
	v_mfma_i32_16x16x64_i8 v[34:37], v[194:197], v[210:213], v[34:37]
	v_mfma_i32_16x16x64_i8 v[26:29], v[186:189], v[222:225], v[26:29]
	v_mfma_i32_16x16x64_i8 v[18:21], v[194:197], v[222:225], v[18:21]
	v_mfma_i32_16x16x64_i8 v[10:13], v[186:189], v[230:233], v[10:13]
	v_mfma_i32_16x16x64_i8 v[2:5], v[194:197], v[230:233], v[2:5]
	s_barrier
	s_add_i32 s21, s21, 2
	s_add_u32 s13, s13, 0x100
	s_addc_u32 s15, s15, 0
	s_add_u32 s24, s24, 0x100
	s_addc_u32 s25, s25, 0
	s_cmp_gt_u32 s21, 13
	s_cbranch_scc0 .LBB0_1332
	s_and_b64 vcc, exec, s[10:11]
	s_cbranch_vccz .LBB0_1335
	s_barrier
